# K-loop LDS-DMA loads of the up and W_in GEMMs use SGPR base + 32-bit VGPR offset (no per-load 64-bit VALU address add), on top of the handoff priority edit
# speedup vs baseline: 1.0020x; 1.0020x over previous
.LBB0_159:
	s_add_u32 s0, s22, 0xfff80080
	s_addc_u32 s1, s23, -1
	s_add_i32 s51, 0, 0x10000
	s_cmp_eq_u32 s50, 28
	s_cselect_b32 s27, s15, s1
	s_cselect_b32 s26, s46, s0
	v_add_u32_e32 v140, s51, v143
	s_cselect_b32 s25, s13, s49
	s_cselect_b32 s24, s47, s48
	s_add_i32 s0, 0, 0x14000
	ds_read_b128 v[146:149], v140
	ds_read_b128 v[150:153], v140 offset:1024
	ds_read_b128 v[154:157], v140 offset:2048
	ds_read_b128 v[158:161], v140 offset:3072
	v_add_u32_e32 v140, s0, v143
	ds_read_b128 v[162:165], v140
	ds_read_b128 v[166:169], v140 offset:1024
	ds_read_b128 v[170:173], v140 offset:2048
	ds_read_b128 v[174:177], v140 offset:3072
	s_add_i32 m0, s35, 0xc000
	ds_read_b128 v[178:181], v144
	ds_read_b128 v[182:185], v144 offset:1024
	ds_read_b128 v[192:195], v144 offset:2048
	ds_read_b128 v[196:199], v144 offset:3072
	ds_read_b128 v[200:203], v144 offset:4096
	ds_read_b128 v[204:207], v144 offset:5120
	ds_read_b128 v[208:211], v144 offset:6144
	ds_read_b128 v[212:215], v144 offset:7168
	global_load_lds_dwordx4 v136, s[22:23]
	s_add_i32 m0, s35, 0xe000
	s_nop 0
	global_load_lds_dwordx4 v138, s[22:23]
	s_waitcnt vmcnt(8)
	s_waitcnt lgkmcnt(0)
	s_setprio 1
	s_barrier

	v_mfma_f32_16x16x32_bf16 v[126:129], v[146:149], v[178:181], v[126:129]
	v_mfma_f32_16x16x32_bf16 v[118:121], v[154:157], v[178:181], v[118:121]
	v_mfma_f32_16x16x32_bf16 v[110:113], v[146:149], v[192:195], v[110:113]
	v_mfma_f32_16x16x32_bf16 v[102:105], v[154:157], v[192:195], v[102:105]
	v_mfma_f32_16x16x32_bf16 v[94:97], v[146:149], v[200:203], v[94:97]
	v_mfma_f32_16x16x32_bf16 v[86:89], v[154:157], v[200:203], v[86:89]
	v_mfma_f32_16x16x32_bf16 v[78:81], v[146:149], v[208:211], v[78:81]
	v_mfma_f32_16x16x32_bf16 v[70:73], v[154:157], v[208:211], v[70:73]
	v_mfma_f32_16x16x32_bf16 v[126:129], v[150:153], v[182:185], v[126:129]
	v_mfma_f32_16x16x32_bf16 v[118:121], v[158:161], v[182:185], v[118:121]
	v_mfma_f32_16x16x32_bf16 v[110:113], v[150:153], v[196:199], v[110:113]
	v_mfma_f32_16x16x32_bf16 v[102:105], v[158:161], v[196:199], v[102:105]
	v_mfma_f32_16x16x32_bf16 v[94:97], v[150:153], v[204:207], v[94:97]
	v_mfma_f32_16x16x32_bf16 v[86:89], v[158:161], v[204:207], v[86:89]
	v_mfma_f32_16x16x32_bf16 v[78:81], v[150:153], v[212:215], v[78:81]
	v_mfma_f32_16x16x32_bf16 v[70:73], v[158:161], v[212:215], v[70:73]


	v_mfma_f32_16x16x32_bf16 v[122:125], v[162:165], v[178:181], v[122:125]
	v_mfma_f32_16x16x32_bf16 v[114:117], v[170:173], v[178:181], v[114:117]
	v_mfma_f32_16x16x32_bf16 v[106:109], v[162:165], v[192:195], v[106:109]
	v_mfma_f32_16x16x32_bf16 v[98:101], v[170:173], v[192:195], v[98:101]
	v_mfma_f32_16x16x32_bf16 v[90:93], v[162:165], v[200:203], v[90:93]
	v_mfma_f32_16x16x32_bf16 v[82:85], v[170:173], v[200:203], v[82:85]
	v_mfma_f32_16x16x32_bf16 v[74:77], v[162:165], v[208:211], v[74:77]
	v_mfma_f32_16x16x32_bf16 v[66:69], v[170:173], v[208:211], v[66:69]
	v_mfma_f32_16x16x32_bf16 v[122:125], v[166:169], v[182:185], v[122:125]
	v_mfma_f32_16x16x32_bf16 v[114:117], v[174:177], v[182:185], v[114:117]
	v_mfma_f32_16x16x32_bf16 v[106:109], v[166:169], v[196:199], v[106:109]
	v_mfma_f32_16x16x32_bf16 v[98:101], v[174:177], v[196:199], v[98:101]
	v_mfma_f32_16x16x32_bf16 v[90:93], v[166:169], v[204:207], v[90:93]
	v_mfma_f32_16x16x32_bf16 v[82:85], v[174:177], v[204:207], v[82:85]
	v_mfma_f32_16x16x32_bf16 v[74:77], v[166:169], v[212:215], v[74:77]
	v_mfma_f32_16x16x32_bf16 v[66:69], v[174:177], v[212:215], v[66:69]
	s_barrier
	s_setprio 0
	s_add_i32 s1, s51, s31
	s_mov_b32 m0, s1
	ds_read_b128 v[178:181], v144 offset:16384
	ds_read_b128 v[182:185], v144 offset:17408
	ds_read_b128 v[192:195], v144 offset:18432
	ds_read_b128 v[196:199], v144 offset:19456
	ds_read_b128 v[200:203], v144 offset:20480
	ds_read_b128 v[204:207], v144 offset:21504
	ds_read_b128 v[208:211], v144 offset:22528
	ds_read_b128 v[212:215], v144 offset:23552
	global_load_lds_dwordx4 v186, s[24:25]
	s_add_i32 m0, s1, 0x2000
	s_add_u32 s52, s24, 0x80000
	s_addc_u32 s53, s25, 0
	s_add_i32 s0, s0, s31
	global_load_lds_dwordx4 v130, s[24:25]
	s_mov_b32 m0, s0
	s_nop 0
	global_load_lds_dwordx4 v186, s[52:53]
	s_add_i32 m0, s0, 0x2000
	s_nop 0
	global_load_lds_dwordx4 v130, s[52:53]
	s_mov_b32 m0, s35
	s_nop 0
	global_load_lds_dwordx4 v134, s[26:27]
	s_mov_b32 m0, s36
	s_nop 0
	global_load_lds_dwordx4 v132, s[26:27]
	s_waitcnt vmcnt(8)
	s_waitcnt lgkmcnt(0)
	s_setprio 1
	s_barrier

	v_mfma_f32_16x16x32_bf16 v[62:65], v[146:149], v[178:181], v[62:65]
	v_mfma_f32_16x16x32_bf16 v[54:57], v[154:157], v[178:181], v[54:57]
	v_mfma_f32_16x16x32_bf16 v[46:49], v[146:149], v[192:195], v[46:49]
	v_mfma_f32_16x16x32_bf16 v[38:41], v[154:157], v[192:195], v[38:41]
	v_mfma_f32_16x16x32_bf16 v[30:33], v[146:149], v[200:203], v[30:33]
	v_mfma_f32_16x16x32_bf16 v[22:25], v[154:157], v[200:203], v[22:25]
	v_mfma_f32_16x16x32_bf16 v[14:17], v[146:149], v[208:211], v[14:17]
	v_mfma_f32_16x16x32_bf16 v[6:9], v[154:157], v[208:211], v[6:9]
	v_mfma_f32_16x16x32_bf16 v[62:65], v[150:153], v[182:185], v[62:65]
	v_mfma_f32_16x16x32_bf16 v[54:57], v[158:161], v[182:185], v[54:57]
	v_mfma_f32_16x16x32_bf16 v[46:49], v[150:153], v[196:199], v[46:49]
	v_mfma_f32_16x16x32_bf16 v[38:41], v[158:161], v[196:199], v[38:41]
	v_mfma_f32_16x16x32_bf16 v[30:33], v[150:153], v[204:207], v[30:33]
	v_mfma_f32_16x16x32_bf16 v[22:25], v[158:161], v[204:207], v[22:25]
	v_mfma_f32_16x16x32_bf16 v[14:17], v[150:153], v[212:215], v[14:17]
	v_mfma_f32_16x16x32_bf16 v[6:9], v[158:161], v[212:215], v[6:9]


	v_mfma_f32_16x16x32_bf16 v[58:61], v[162:165], v[178:181], v[58:61]
	v_mfma_f32_16x16x32_bf16 v[50:53], v[170:173], v[178:181], v[50:53]
	v_mfma_f32_16x16x32_bf16 v[42:45], v[162:165], v[192:195], v[42:45]
	v_mfma_f32_16x16x32_bf16 v[34:37], v[170:173], v[192:195], v[34:37]
	v_mfma_f32_16x16x32_bf16 v[26:29], v[162:165], v[200:203], v[26:29]
	v_mfma_f32_16x16x32_bf16 v[18:21], v[170:173], v[200:203], v[18:21]
	v_mfma_f32_16x16x32_bf16 v[10:13], v[162:165], v[208:211], v[10:13]
	v_mfma_f32_16x16x32_bf16 v[2:5], v[170:173], v[208:211], v[2:5]
	v_mfma_f32_16x16x32_bf16 v[58:61], v[166:169], v[182:185], v[58:61]
	v_mfma_f32_16x16x32_bf16 v[50:53], v[174:177], v[182:185], v[50:53]
	v_mfma_f32_16x16x32_bf16 v[42:45], v[166:169], v[196:199], v[42:45]
	v_mfma_f32_16x16x32_bf16 v[34:37], v[174:177], v[196:199], v[34:37]
	v_mfma_f32_16x16x32_bf16 v[26:29], v[166:169], v[204:207], v[26:29]
	v_mfma_f32_16x16x32_bf16 v[18:21], v[174:177], v[204:207], v[18:21]
	v_mfma_f32_16x16x32_bf16 v[10:13], v[166:169], v[212:215], v[10:13]
	v_mfma_f32_16x16x32_bf16 v[2:5], v[174:177], v[212:215], v[2:5]
	s_barrier
	s_setprio 0
	s_add_i32 s0, 0, 0x18000
	v_add_u32_e32 v145, s0, v143
	s_add_i32 s1, 0, 0x1c000
	ds_read_b128 v[146:149], v145
	ds_read_b128 v[150:153], v145 offset:1024
	ds_read_b128 v[154:157], v145 offset:2048
	ds_read_b128 v[158:161], v145 offset:3072
	v_add_u32_e32 v145, s1, v143
	ds_read_b128 v[162:165], v145
	ds_read_b128 v[166:169], v145 offset:1024
	ds_read_b128 v[170:173], v145 offset:2048
	ds_read_b128 v[174:177], v145 offset:3072
	s_add_u32 s26, s26, 0x80000
	s_addc_u32 s27, s27, 0
	s_mov_b32 m0, s37
	ds_read_b128 v[178:181], v144 offset:32768
	ds_read_b128 v[182:185], v144 offset:33792
	ds_read_b128 v[192:195], v144 offset:34816
	ds_read_b128 v[196:199], v144 offset:35840
	ds_read_b128 v[200:203], v144 offset:36864
	ds_read_b128 v[204:207], v144 offset:37888
	ds_read_b128 v[208:211], v144 offset:38912
	ds_read_b128 v[212:215], v144 offset:39936
	global_load_lds_dwordx4 v134, s[26:27]
	s_mov_b32 m0, s38
	s_nop 0
	global_load_lds_dwordx4 v132, s[26:27]
	s_waitcnt vmcnt(8)
	s_waitcnt lgkmcnt(0)
	s_setprio 1
	s_barrier

	v_mfma_f32_16x16x32_bf16 v[126:129], v[146:149], v[178:181], v[126:129]
	v_mfma_f32_16x16x32_bf16 v[118:121], v[154:157], v[178:181], v[118:121]
	v_mfma_f32_16x16x32_bf16 v[110:113], v[146:149], v[192:195], v[110:113]
	v_mfma_f32_16x16x32_bf16 v[102:105], v[154:157], v[192:195], v[102:105]
	v_mfma_f32_16x16x32_bf16 v[94:97], v[146:149], v[200:203], v[94:97]
	v_mfma_f32_16x16x32_bf16 v[86:89], v[154:157], v[200:203], v[86:89]
	v_mfma_f32_16x16x32_bf16 v[78:81], v[146:149], v[208:211], v[78:81]
	v_mfma_f32_16x16x32_bf16 v[70:73], v[154:157], v[208:211], v[70:73]
	v_mfma_f32_16x16x32_bf16 v[126:129], v[150:153], v[182:185], v[126:129]
	v_mfma_f32_16x16x32_bf16 v[118:121], v[158:161], v[182:185], v[118:121]
	v_mfma_f32_16x16x32_bf16 v[110:113], v[150:153], v[196:199], v[110:113]
	v_mfma_f32_16x16x32_bf16 v[102:105], v[158:161], v[196:199], v[102:105]
	v_mfma_f32_16x16x32_bf16 v[94:97], v[150:153], v[204:207], v[94:97]
	v_mfma_f32_16x16x32_bf16 v[86:89], v[158:161], v[204:207], v[86:89]
	v_mfma_f32_16x16x32_bf16 v[78:81], v[150:153], v[212:215], v[78:81]
	v_mfma_f32_16x16x32_bf16 v[70:73], v[158:161], v[212:215], v[70:73]


	v_mfma_f32_16x16x32_bf16 v[122:125], v[162:165], v[178:181], v[122:125]
	v_mfma_f32_16x16x32_bf16 v[114:117], v[170:173], v[178:181], v[114:117]
	v_mfma_f32_16x16x32_bf16 v[106:109], v[162:165], v[192:195], v[106:109]
	v_mfma_f32_16x16x32_bf16 v[98:101], v[170:173], v[192:195], v[98:101]
	v_mfma_f32_16x16x32_bf16 v[90:93], v[162:165], v[200:203], v[90:93]
	v_mfma_f32_16x16x32_bf16 v[82:85], v[170:173], v[200:203], v[82:85]
	v_mfma_f32_16x16x32_bf16 v[74:77], v[162:165], v[208:211], v[74:77]
	v_mfma_f32_16x16x32_bf16 v[66:69], v[170:173], v[208:211], v[66:69]
	v_mfma_f32_16x16x32_bf16 v[122:125], v[166:169], v[182:185], v[122:125]
	v_mfma_f32_16x16x32_bf16 v[114:117], v[174:177], v[182:185], v[114:117]
	v_mfma_f32_16x16x32_bf16 v[106:109], v[166:169], v[196:199], v[106:109]
	v_mfma_f32_16x16x32_bf16 v[98:101], v[174:177], v[196:199], v[98:101]
	v_mfma_f32_16x16x32_bf16 v[90:93], v[166:169], v[204:207], v[90:93]
	v_mfma_f32_16x16x32_bf16 v[82:85], v[174:177], v[204:207], v[82:85]
	v_mfma_f32_16x16x32_bf16 v[74:77], v[166:169], v[212:215], v[74:77]
	v_mfma_f32_16x16x32_bf16 v[66:69], v[174:177], v[212:215], v[66:69]
	s_barrier
	s_setprio 0
	s_add_i32 s0, s0, s31
	s_mov_b32 m0, s0
	ds_read_b128 v[178:181], v144 offset:49152
	ds_read_b128 v[182:185], v144 offset:50176
	ds_read_b128 v[192:195], v144 offset:51200
	ds_read_b128 v[196:199], v144 offset:52224
	ds_read_b128 v[200:203], v144 offset:53248
	ds_read_b128 v[204:207], v144 offset:54272
	ds_read_b128 v[208:211], v144 offset:55296
	ds_read_b128 v[212:215], v144 offset:56320
	s_add_u32 s100, s24, 0x80
	s_addc_u32 s101, s25, 0
	global_load_lds_dwordx4 v186, s[100:101]
	s_add_i32 m0, s0, 0x2000
	s_add_u32 s24, s24, 0x80080
	s_addc_u32 s25, s25, 0
	s_add_i32 s0, s1, s31
	s_add_u32 s100, s24, 0xfff80000
	s_addc_u32 s101, s25, -1
	global_load_lds_dwordx4 v130, s[100:101]
	s_mov_b32 m0, s0
	s_nop 0
	global_load_lds_dwordx4 v186, s[24:25]
	s_add_i32 m0, s0, 0x2000
	s_nop 0
	global_load_lds_dwordx4 v130, s[24:25]
	s_mov_b32 m0, s39
	s_nop 0
	s_add_u32 s100, s26, 0xfff80080
	s_addc_u32 s101, s27, -1
	global_load_lds_dwordx4 v134, s[100:101]
	s_mov_b32 m0, s40
	s_nop 0
	s_add_u32 s100, s26, 0xfff80080
	s_addc_u32 s101, s27, -1
	global_load_lds_dwordx4 v132, s[100:101]
	s_waitcnt vmcnt(8)
	s_waitcnt lgkmcnt(0)
	s_setprio 1
	s_barrier

	v_mfma_f32_16x16x32_bf16 v[62:65], v[146:149], v[178:181], v[62:65]
	v_mfma_f32_16x16x32_bf16 v[54:57], v[154:157], v[178:181], v[54:57]
	v_mfma_f32_16x16x32_bf16 v[46:49], v[146:149], v[192:195], v[46:49]
	v_mfma_f32_16x16x32_bf16 v[38:41], v[154:157], v[192:195], v[38:41]
	v_mfma_f32_16x16x32_bf16 v[30:33], v[146:149], v[200:203], v[30:33]
	v_mfma_f32_16x16x32_bf16 v[22:25], v[154:157], v[200:203], v[22:25]
	v_mfma_f32_16x16x32_bf16 v[14:17], v[146:149], v[208:211], v[14:17]
	v_mfma_f32_16x16x32_bf16 v[6:9], v[154:157], v[208:211], v[6:9]
	v_mfma_f32_16x16x32_bf16 v[62:65], v[150:153], v[182:185], v[62:65]
	v_mfma_f32_16x16x32_bf16 v[54:57], v[158:161], v[182:185], v[54:57]
	v_mfma_f32_16x16x32_bf16 v[46:49], v[150:153], v[196:199], v[46:49]
	v_mfma_f32_16x16x32_bf16 v[38:41], v[158:161], v[196:199], v[38:41]
	v_mfma_f32_16x16x32_bf16 v[30:33], v[150:153], v[204:207], v[30:33]
	v_mfma_f32_16x16x32_bf16 v[22:25], v[158:161], v[204:207], v[22:25]
	v_mfma_f32_16x16x32_bf16 v[14:17], v[150:153], v[212:215], v[14:17]
	v_mfma_f32_16x16x32_bf16 v[6:9], v[158:161], v[212:215], v[6:9]


	v_mfma_f32_16x16x32_bf16 v[58:61], v[162:165], v[178:181], v[58:61]
	v_mfma_f32_16x16x32_bf16 v[50:53], v[170:173], v[178:181], v[50:53]
	v_mfma_f32_16x16x32_bf16 v[42:45], v[162:165], v[192:195], v[42:45]
	v_mfma_f32_16x16x32_bf16 v[34:37], v[170:173], v[192:195], v[34:37]
	v_mfma_f32_16x16x32_bf16 v[26:29], v[162:165], v[200:203], v[26:29]
	v_mfma_f32_16x16x32_bf16 v[18:21], v[170:173], v[200:203], v[18:21]
	v_mfma_f32_16x16x32_bf16 v[10:13], v[162:165], v[208:211], v[10:13]
	v_mfma_f32_16x16x32_bf16 v[2:5], v[170:173], v[208:211], v[2:5]
	v_mfma_f32_16x16x32_bf16 v[58:61], v[166:169], v[182:185], v[58:61]
	v_mfma_f32_16x16x32_bf16 v[50:53], v[174:177], v[182:185], v[50:53]
	v_mfma_f32_16x16x32_bf16 v[42:45], v[166:169], v[196:199], v[42:45]
	v_mfma_f32_16x16x32_bf16 v[34:37], v[174:177], v[196:199], v[34:37]
	v_mfma_f32_16x16x32_bf16 v[26:29], v[166:169], v[204:207], v[26:29]
	v_mfma_f32_16x16x32_bf16 v[18:21], v[174:177], v[204:207], v[18:21]
	v_mfma_f32_16x16x32_bf16 v[10:13], v[166:169], v[212:215], v[10:13]
	v_mfma_f32_16x16x32_bf16 v[2:5], v[174:177], v[212:215], v[2:5]
	s_barrier
	s_setprio 0
	s_add_i32 s50, s50, 2
	s_add_u32 s22, s22, 0x100
	s_addc_u32 s23, s23, 0
	s_add_u32 s48, s48, 0x100
	s_addc_u32 s49, s49, 0
	s_cmp_gt_u32 s50, 29
	s_cbranch_scc0 .LBB0_159
	s_and_b64 vcc, exec, s[10:11]
	s_cbranch_vccz .LBB0_162
	s_barrier

.LBB0_443:
	s_add_u32 s0, s26, 0xfff80080
	s_addc_u32 s1, s27, -1
	s_add_i32 s56, 0, 0x10000
	s_cmp_eq_u32 s55, 28
	s_cselect_b32 s31, s19, s1
	s_cselect_b32 s30, s51, s0
	v_add_u32_e32 v140, s56, v144
	s_cselect_b32 s29, s17, s54
	s_cselect_b32 s28, s52, s53
	s_add_i32 s0, 0, 0x14000
	ds_read_b128 v[146:149], v140
	ds_read_b128 v[150:153], v140 offset:1024
	ds_read_b128 v[154:157], v140 offset:2048
	ds_read_b128 v[158:161], v140 offset:3072
	v_add_u32_e32 v140, s0, v144
	ds_read_b128 v[162:165], v140
	ds_read_b128 v[166:169], v140 offset:1024
	ds_read_b128 v[170:173], v140 offset:2048
	ds_read_b128 v[174:177], v140 offset:3072
	s_add_i32 m0, s25, 0xc000
	ds_read_b128 v[178:181], v145
	ds_read_b128 v[182:185], v145 offset:1024
	ds_read_b128 v[192:195], v145 offset:2048
	ds_read_b128 v[196:199], v145 offset:3072
	ds_read_b128 v[200:203], v145 offset:4096
	ds_read_b128 v[204:207], v145 offset:5120
	ds_read_b128 v[208:211], v145 offset:6144
	ds_read_b128 v[212:215], v145 offset:7168
	global_load_lds_dwordx4 v136, s[26:27]
	s_add_i32 m0, s25, 0xe000
	s_nop 0
	global_load_lds_dwordx4 v138, s[26:27]
	s_waitcnt vmcnt(8)
	s_waitcnt lgkmcnt(0)
	s_setprio 1
	s_barrier

	v_mfma_f32_16x16x32_bf16 v[126:129], v[146:149], v[178:181], v[126:129]
	v_mfma_f32_16x16x32_bf16 v[122:125], v[154:157], v[178:181], v[122:125]
	v_mfma_f32_16x16x32_bf16 v[114:117], v[146:149], v[192:195], v[114:117]
	v_mfma_f32_16x16x32_bf16 v[106:109], v[154:157], v[192:195], v[106:109]
	v_mfma_f32_16x16x32_bf16 v[98:101], v[146:149], v[200:203], v[98:101]
	v_mfma_f32_16x16x32_bf16 v[90:93], v[154:157], v[200:203], v[90:93]
	v_mfma_f32_16x16x32_bf16 v[82:85], v[146:149], v[208:211], v[82:85]
	v_mfma_f32_16x16x32_bf16 v[74:77], v[154:157], v[208:211], v[74:77]
	v_mfma_f32_16x16x32_bf16 v[126:129], v[150:153], v[182:185], v[126:129]
	v_mfma_f32_16x16x32_bf16 v[122:125], v[158:161], v[182:185], v[122:125]
	v_mfma_f32_16x16x32_bf16 v[114:117], v[150:153], v[196:199], v[114:117]
	v_mfma_f32_16x16x32_bf16 v[106:109], v[158:161], v[196:199], v[106:109]
	v_mfma_f32_16x16x32_bf16 v[98:101], v[150:153], v[204:207], v[98:101]
	v_mfma_f32_16x16x32_bf16 v[90:93], v[158:161], v[204:207], v[90:93]
	v_mfma_f32_16x16x32_bf16 v[82:85], v[150:153], v[212:215], v[82:85]
	v_mfma_f32_16x16x32_bf16 v[74:77], v[158:161], v[212:215], v[74:77]


	v_mfma_f32_16x16x32_bf16 v[118:121], v[162:165], v[178:181], v[118:121]
	v_mfma_f32_16x16x32_bf16 v[110:113], v[170:173], v[178:181], v[110:113]
	v_mfma_f32_16x16x32_bf16 v[102:105], v[162:165], v[192:195], v[102:105]
	v_mfma_f32_16x16x32_bf16 v[94:97], v[170:173], v[192:195], v[94:97]
	v_mfma_f32_16x16x32_bf16 v[86:89], v[162:165], v[200:203], v[86:89]
	v_mfma_f32_16x16x32_bf16 v[78:81], v[170:173], v[200:203], v[78:81]
	v_mfma_f32_16x16x32_bf16 v[70:73], v[162:165], v[208:211], v[70:73]
	v_mfma_f32_16x16x32_bf16 v[66:69], v[170:173], v[208:211], v[66:69]
	v_mfma_f32_16x16x32_bf16 v[118:121], v[166:169], v[182:185], v[118:121]
	v_mfma_f32_16x16x32_bf16 v[110:113], v[174:177], v[182:185], v[110:113]
	v_mfma_f32_16x16x32_bf16 v[102:105], v[166:169], v[196:199], v[102:105]
	v_mfma_f32_16x16x32_bf16 v[94:97], v[174:177], v[196:199], v[94:97]
	v_mfma_f32_16x16x32_bf16 v[86:89], v[166:169], v[204:207], v[86:89]
	v_mfma_f32_16x16x32_bf16 v[78:81], v[174:177], v[204:207], v[78:81]
	v_mfma_f32_16x16x32_bf16 v[70:73], v[166:169], v[212:215], v[70:73]
	v_mfma_f32_16x16x32_bf16 v[66:69], v[174:177], v[212:215], v[66:69]
	s_barrier
	s_setprio 0
	s_add_i32 s1, s56, s39
	s_mov_b32 m0, s1
	ds_read_b128 v[178:181], v145 offset:16384
	ds_read_b128 v[182:185], v145 offset:17408
	ds_read_b128 v[192:195], v145 offset:18432
	ds_read_b128 v[196:199], v145 offset:19456
	ds_read_b128 v[200:203], v145 offset:20480
	ds_read_b128 v[204:207], v145 offset:21504
	ds_read_b128 v[208:211], v145 offset:22528
	ds_read_b128 v[212:215], v145 offset:23552
	global_load_lds_dwordx4 v186, s[28:29]
	s_add_i32 m0, s1, 0x2000
	s_add_u32 s56, s28, 0x80000
	s_addc_u32 s57, s29, 0
	s_add_i32 s0, s0, s39
	global_load_lds_dwordx4 v130, s[28:29]
	s_mov_b32 m0, s0
	s_nop 0
	global_load_lds_dwordx4 v186, s[56:57]
	s_add_i32 m0, s0, 0x2000
	s_nop 0
	global_load_lds_dwordx4 v130, s[56:57]
	s_mov_b32 m0, s25
	s_nop 0
	global_load_lds_dwordx4 v134, s[30:31]
	s_mov_b32 m0, s40
	s_nop 0
	global_load_lds_dwordx4 v132, s[30:31]
	s_waitcnt vmcnt(8)
	s_waitcnt lgkmcnt(0)
	s_setprio 1
	s_barrier

	v_mfma_f32_16x16x32_bf16 v[62:65], v[146:149], v[178:181], v[62:65]
	v_mfma_f32_16x16x32_bf16 v[58:61], v[154:157], v[178:181], v[58:61]
	v_mfma_f32_16x16x32_bf16 v[50:53], v[146:149], v[192:195], v[50:53]
	v_mfma_f32_16x16x32_bf16 v[42:45], v[154:157], v[192:195], v[42:45]
	v_mfma_f32_16x16x32_bf16 v[34:37], v[146:149], v[200:203], v[34:37]
	v_mfma_f32_16x16x32_bf16 v[26:29], v[154:157], v[200:203], v[26:29]
	v_mfma_f32_16x16x32_bf16 v[18:21], v[146:149], v[208:211], v[18:21]
	v_mfma_f32_16x16x32_bf16 v[10:13], v[154:157], v[208:211], v[10:13]
	v_mfma_f32_16x16x32_bf16 v[62:65], v[150:153], v[182:185], v[62:65]
	v_mfma_f32_16x16x32_bf16 v[58:61], v[158:161], v[182:185], v[58:61]
	v_mfma_f32_16x16x32_bf16 v[50:53], v[150:153], v[196:199], v[50:53]
	v_mfma_f32_16x16x32_bf16 v[42:45], v[158:161], v[196:199], v[42:45]
	v_mfma_f32_16x16x32_bf16 v[34:37], v[150:153], v[204:207], v[34:37]
	v_mfma_f32_16x16x32_bf16 v[26:29], v[158:161], v[204:207], v[26:29]
	v_mfma_f32_16x16x32_bf16 v[18:21], v[150:153], v[212:215], v[18:21]
	v_mfma_f32_16x16x32_bf16 v[10:13], v[158:161], v[212:215], v[10:13]


	v_mfma_f32_16x16x32_bf16 v[54:57], v[162:165], v[178:181], v[54:57]
	v_mfma_f32_16x16x32_bf16 v[46:49], v[170:173], v[178:181], v[46:49]
	v_mfma_f32_16x16x32_bf16 v[38:41], v[162:165], v[192:195], v[38:41]
	v_mfma_f32_16x16x32_bf16 v[30:33], v[170:173], v[192:195], v[30:33]
	v_mfma_f32_16x16x32_bf16 v[22:25], v[162:165], v[200:203], v[22:25]
	v_mfma_f32_16x16x32_bf16 v[14:17], v[170:173], v[200:203], v[14:17]
	v_mfma_f32_16x16x32_bf16 v[6:9], v[162:165], v[208:211], v[6:9]
	v_mfma_f32_16x16x32_bf16 v[2:5], v[170:173], v[208:211], v[2:5]
	v_mfma_f32_16x16x32_bf16 v[54:57], v[166:169], v[182:185], v[54:57]
	v_mfma_f32_16x16x32_bf16 v[46:49], v[174:177], v[182:185], v[46:49]
	v_mfma_f32_16x16x32_bf16 v[38:41], v[166:169], v[196:199], v[38:41]
	v_mfma_f32_16x16x32_bf16 v[30:33], v[174:177], v[196:199], v[30:33]
	v_mfma_f32_16x16x32_bf16 v[22:25], v[166:169], v[204:207], v[22:25]
	v_mfma_f32_16x16x32_bf16 v[14:17], v[174:177], v[204:207], v[14:17]
	v_mfma_f32_16x16x32_bf16 v[6:9], v[166:169], v[212:215], v[6:9]
	v_mfma_f32_16x16x32_bf16 v[2:5], v[174:177], v[212:215], v[2:5]
	s_barrier
	s_setprio 0
	s_add_i32 s0, 0, 0x18000
	s_add_i32 s1, 0, 0x1c000
	v_add_u32_e32 v158, s0, v144
	v_add_u32_e32 v174, s1, v144
	ds_read_b128 v[146:149], v158
	ds_read_b128 v[150:153], v158 offset:1024
	ds_read_b128 v[154:157], v158 offset:2048
	ds_read_b128 v[158:161], v158 offset:3072
	ds_read_b128 v[162:165], v174
	ds_read_b128 v[166:169], v174 offset:1024
	ds_read_b128 v[170:173], v174 offset:2048
	ds_read_b128 v[174:177], v174 offset:3072
	s_add_u32 s30, s30, 0x80000
	s_addc_u32 s31, s31, 0
	s_mov_b32 m0, s41
	ds_read_b128 v[178:181], v145 offset:32768
	ds_read_b128 v[182:185], v145 offset:33792
	ds_read_b128 v[192:195], v145 offset:34816
	ds_read_b128 v[196:199], v145 offset:35840
	ds_read_b128 v[200:203], v145 offset:36864
	ds_read_b128 v[204:207], v145 offset:37888
	ds_read_b128 v[208:211], v145 offset:38912
	ds_read_b128 v[212:215], v145 offset:39936
	global_load_lds_dwordx4 v134, s[30:31]
	s_mov_b32 m0, s42
	s_nop 0
	global_load_lds_dwordx4 v132, s[30:31]
	s_waitcnt vmcnt(8)
	s_waitcnt lgkmcnt(0)
	s_setprio 1
	s_barrier

	v_mfma_f32_16x16x32_bf16 v[126:129], v[146:149], v[178:181], v[126:129]
	v_mfma_f32_16x16x32_bf16 v[122:125], v[154:157], v[178:181], v[122:125]
	v_mfma_f32_16x16x32_bf16 v[114:117], v[146:149], v[192:195], v[114:117]
	v_mfma_f32_16x16x32_bf16 v[106:109], v[154:157], v[192:195], v[106:109]
	v_mfma_f32_16x16x32_bf16 v[98:101], v[146:149], v[200:203], v[98:101]
	v_mfma_f32_16x16x32_bf16 v[90:93], v[154:157], v[200:203], v[90:93]
	v_mfma_f32_16x16x32_bf16 v[82:85], v[146:149], v[208:211], v[82:85]
	v_mfma_f32_16x16x32_bf16 v[74:77], v[154:157], v[208:211], v[74:77]
	v_mfma_f32_16x16x32_bf16 v[126:129], v[150:153], v[182:185], v[126:129]
	v_mfma_f32_16x16x32_bf16 v[122:125], v[158:161], v[182:185], v[122:125]
	v_mfma_f32_16x16x32_bf16 v[114:117], v[150:153], v[196:199], v[114:117]
	v_mfma_f32_16x16x32_bf16 v[106:109], v[158:161], v[196:199], v[106:109]
	v_mfma_f32_16x16x32_bf16 v[98:101], v[150:153], v[204:207], v[98:101]
	v_mfma_f32_16x16x32_bf16 v[90:93], v[158:161], v[204:207], v[90:93]
	v_mfma_f32_16x16x32_bf16 v[82:85], v[150:153], v[212:215], v[82:85]
	v_mfma_f32_16x16x32_bf16 v[74:77], v[158:161], v[212:215], v[74:77]


	v_mfma_f32_16x16x32_bf16 v[118:121], v[162:165], v[178:181], v[118:121]
	v_mfma_f32_16x16x32_bf16 v[110:113], v[170:173], v[178:181], v[110:113]
	v_mfma_f32_16x16x32_bf16 v[102:105], v[162:165], v[192:195], v[102:105]
	v_mfma_f32_16x16x32_bf16 v[94:97], v[170:173], v[192:195], v[94:97]
	v_mfma_f32_16x16x32_bf16 v[86:89], v[162:165], v[200:203], v[86:89]
	v_mfma_f32_16x16x32_bf16 v[78:81], v[170:173], v[200:203], v[78:81]
	v_mfma_f32_16x16x32_bf16 v[70:73], v[162:165], v[208:211], v[70:73]
	v_mfma_f32_16x16x32_bf16 v[66:69], v[170:173], v[208:211], v[66:69]
	v_mfma_f32_16x16x32_bf16 v[118:121], v[166:169], v[182:185], v[118:121]
	v_mfma_f32_16x16x32_bf16 v[110:113], v[174:177], v[182:185], v[110:113]
	v_mfma_f32_16x16x32_bf16 v[102:105], v[166:169], v[196:199], v[102:105]
	v_mfma_f32_16x16x32_bf16 v[94:97], v[174:177], v[196:199], v[94:97]
	v_mfma_f32_16x16x32_bf16 v[86:89], v[166:169], v[204:207], v[86:89]
	v_mfma_f32_16x16x32_bf16 v[78:81], v[174:177], v[204:207], v[78:81]
	v_mfma_f32_16x16x32_bf16 v[70:73], v[166:169], v[212:215], v[70:73]
	v_mfma_f32_16x16x32_bf16 v[66:69], v[174:177], v[212:215], v[66:69]
	s_barrier
	s_setprio 0
	s_add_i32 s0, s0, s39
	s_mov_b32 m0, s0
	ds_read_b128 v[178:181], v145 offset:49152
	ds_read_b128 v[182:185], v145 offset:50176
	ds_read_b128 v[192:195], v145 offset:51200
	ds_read_b128 v[196:199], v145 offset:52224
	ds_read_b128 v[200:203], v145 offset:53248
	ds_read_b128 v[204:207], v145 offset:54272
	ds_read_b128 v[208:211], v145 offset:55296
	ds_read_b128 v[212:215], v145 offset:56320
	s_add_u32 s100, s28, 0x80
	s_addc_u32 s101, s29, 0
	global_load_lds_dwordx4 v186, s[100:101]
	s_add_i32 m0, s0, 0x2000
	s_add_u32 s28, s28, 0x80080
	s_addc_u32 s29, s29, 0
	s_add_i32 s0, s1, s39
	s_add_u32 s100, s28, 0xfff80000
	s_addc_u32 s101, s29, -1
	global_load_lds_dwordx4 v130, s[100:101]
	s_mov_b32 m0, s0
	s_nop 0
	global_load_lds_dwordx4 v186, s[28:29]
	s_add_i32 m0, s0, 0x2000
	s_nop 0
	global_load_lds_dwordx4 v130, s[28:29]
	s_mov_b32 m0, s43
	s_nop 0
	s_add_u32 s100, s30, 0xfff80080
	s_addc_u32 s101, s31, -1
	global_load_lds_dwordx4 v134, s[100:101]
	s_mov_b32 m0, s44
	s_nop 0
	s_add_u32 s100, s30, 0xfff80080
	s_addc_u32 s101, s31, -1
	global_load_lds_dwordx4 v132, s[100:101]
	s_waitcnt vmcnt(8)
	s_waitcnt lgkmcnt(0)
	s_setprio 1
	s_barrier

	v_mfma_f32_16x16x32_bf16 v[62:65], v[146:149], v[178:181], v[62:65]
	v_mfma_f32_16x16x32_bf16 v[58:61], v[154:157], v[178:181], v[58:61]
	v_mfma_f32_16x16x32_bf16 v[50:53], v[146:149], v[192:195], v[50:53]
	v_mfma_f32_16x16x32_bf16 v[42:45], v[154:157], v[192:195], v[42:45]
	v_mfma_f32_16x16x32_bf16 v[34:37], v[146:149], v[200:203], v[34:37]
	v_mfma_f32_16x16x32_bf16 v[26:29], v[154:157], v[200:203], v[26:29]
	v_mfma_f32_16x16x32_bf16 v[18:21], v[146:149], v[208:211], v[18:21]
	v_mfma_f32_16x16x32_bf16 v[10:13], v[154:157], v[208:211], v[10:13]
	v_mfma_f32_16x16x32_bf16 v[62:65], v[150:153], v[182:185], v[62:65]
	v_mfma_f32_16x16x32_bf16 v[58:61], v[158:161], v[182:185], v[58:61]
	v_mfma_f32_16x16x32_bf16 v[50:53], v[150:153], v[196:199], v[50:53]
	v_mfma_f32_16x16x32_bf16 v[42:45], v[158:161], v[196:199], v[42:45]
	v_mfma_f32_16x16x32_bf16 v[34:37], v[150:153], v[204:207], v[34:37]
	v_mfma_f32_16x16x32_bf16 v[26:29], v[158:161], v[204:207], v[26:29]
	v_mfma_f32_16x16x32_bf16 v[18:21], v[150:153], v[212:215], v[18:21]
	v_mfma_f32_16x16x32_bf16 v[10:13], v[158:161], v[212:215], v[10:13]


	v_mfma_f32_16x16x32_bf16 v[54:57], v[162:165], v[178:181], v[54:57]
	v_mfma_f32_16x16x32_bf16 v[46:49], v[170:173], v[178:181], v[46:49]
	v_mfma_f32_16x16x32_bf16 v[38:41], v[162:165], v[192:195], v[38:41]
	v_mfma_f32_16x16x32_bf16 v[30:33], v[170:173], v[192:195], v[30:33]
	v_mfma_f32_16x16x32_bf16 v[22:25], v[162:165], v[200:203], v[22:25]
	v_mfma_f32_16x16x32_bf16 v[14:17], v[170:173], v[200:203], v[14:17]
	v_mfma_f32_16x16x32_bf16 v[6:9], v[162:165], v[208:211], v[6:9]
	v_mfma_f32_16x16x32_bf16 v[2:5], v[170:173], v[208:211], v[2:5]
	v_mfma_f32_16x16x32_bf16 v[54:57], v[166:169], v[182:185], v[54:57]
	v_mfma_f32_16x16x32_bf16 v[46:49], v[174:177], v[182:185], v[46:49]
	v_mfma_f32_16x16x32_bf16 v[38:41], v[166:169], v[196:199], v[38:41]
	v_mfma_f32_16x16x32_bf16 v[30:33], v[174:177], v[196:199], v[30:33]
	v_mfma_f32_16x16x32_bf16 v[22:25], v[166:169], v[204:207], v[22:25]
	v_mfma_f32_16x16x32_bf16 v[14:17], v[174:177], v[204:207], v[14:17]
	v_mfma_f32_16x16x32_bf16 v[6:9], v[166:169], v[212:215], v[6:9]
	v_mfma_f32_16x16x32_bf16 v[2:5], v[174:177], v[212:215], v[2:5]
	s_barrier
	s_setprio 0
	s_add_i32 s55, s55, 2
	s_add_u32 s26, s26, 0x100
	s_addc_u32 s27, s27, 0
	s_add_u32 s53, s53, 0x100
	s_addc_u32 s54, s54, 0
	s_cmp_gt_u32 s55, 29
	s_cbranch_scc0 .LBB0_443
	s_and_b64 vcc, exec, s[14:15]
	s_cbranch_vccz .LBB0_446
	s_barrier

	.amdhsa_kernel _Z3fwd4Args
		.amdhsa_group_segment_fixed_size 0
		.amdhsa_private_segment_fixed_size 0
		.amdhsa_kernarg_size 448
		.amdhsa_user_sgpr_count 2
		.amdhsa_user_sgpr_dispatch_ptr 0
		.amdhsa_user_sgpr_queue_ptr 0
		.amdhsa_user_sgpr_kernarg_segment_ptr 1
		.amdhsa_user_sgpr_dispatch_id 0
		.amdhsa_user_sgpr_kernarg_preload_length 0
		.amdhsa_user_sgpr_kernarg_preload_offset 0
		.amdhsa_user_sgpr_private_segment_size 0
		.amdhsa_uses_dynamic_stack 0
		.amdhsa_enable_private_segment 0
		.amdhsa_system_sgpr_workgroup_id_x 1
		.amdhsa_system_sgpr_workgroup_id_y 0
		.amdhsa_system_sgpr_workgroup_id_z 0
		.amdhsa_system_sgpr_workgroup_info 0
		.amdhsa_system_vgpr_workitem_id 0
		.amdhsa_next_free_vgpr 256
		.amdhsa_next_free_sgpr 102
		.amdhsa_accum_offset 256
		.amdhsa_reserve_vcc 1
		.amdhsa_float_round_mode_32 0
		.amdhsa_float_round_mode_16_64 0
		.amdhsa_float_denorm_mode_32 3
		.amdhsa_float_denorm_mode_16_64 3
		.amdhsa_dx10_clamp 1
		.amdhsa_ieee_mode 1
		.amdhsa_fp16_overflow 0
		.amdhsa_tg_split 0
		.amdhsa_exception_fp_ieee_invalid_op 0
		.amdhsa_exception_fp_denorm_src 0
		.amdhsa_exception_fp_ieee_div_zero 0
		.amdhsa_exception_fp_ieee_overflow 0
		.amdhsa_exception_fp_ieee_underflow 0
		.amdhsa_exception_fp_ieee_inexact 0
		.amdhsa_exception_int_div_zero 0
	.end_amdhsa_kernel

amdhsa.kernels:
  - .agpr_count:     0
    .args:
      - .offset:         0
        .size:           192
        .value_kind:     by_value
      - .offset:         192
        .size:           4
        .value_kind:     hidden_block_count_x
      - .offset:         196
        .size:           4
        .value_kind:     hidden_block_count_y
      - .offset:         200
        .size:           4
        .value_kind:     hidden_block_count_z
      - .offset:         204
        .size:           2
        .value_kind:     hidden_group_size_x
      - .offset:         206
        .size:           2
        .value_kind:     hidden_group_size_y
      - .offset:         208
        .size:           2
        .value_kind:     hidden_group_size_z
      - .offset:         210
        .size:           2
        .value_kind:     hidden_remainder_x
      - .offset:         212
        .size:           2
        .value_kind:     hidden_remainder_y
      - .offset:         214
        .size:           2
        .value_kind:     hidden_remainder_z
      - .offset:         232
        .size:           8
        .value_kind:     hidden_global_offset_x
      - .offset:         240
        .size:           8
        .value_kind:     hidden_global_offset_y
      - .offset:         248
        .size:           8
        .value_kind:     hidden_global_offset_z
      - .offset:         256
        .size:           2
        .value_kind:     hidden_grid_dims
      - .offset:         312
        .size:           4
        .value_kind:     hidden_dynamic_lds_size
    .group_segment_fixed_size: 0
    .kernarg_segment_align: 8
    .kernarg_segment_size: 448
    .language:       OpenCL C
    .language_version:
      - 2
      - 0
    .max_flat_workgroup_size: 512
    .name:           _Z3fwd4Args
    .private_segment_fixed_size: 0
    .sgpr_count:     108
    .sgpr_spill_count: 73
    .symbol:         _Z3fwd4Args.kd
    .uniform_work_group_size: 1
    .uses_dynamic_stack: false
    .vgpr_count:     256
    .vgpr_spill_count: 0
    .wavefront_size: 64
